# LRU gate math: hardware v_sqrt_f32 instead of the 18-instruction correctly-rounded sqrt expansion (argument is 0 or >= 2^-24), both passes, 32 sites
# speedup vs baseline: 1.0085x; 1.0063x over previous
; __device__ __forceinline__ bf16_t f2bf(float f) { return (bf16_t)(cvt_pk_bf16(f, 0.f) & 0xffffu); }
; __device__ __forceinline__ float bf2f(bf16_t b) { return __uint_as_float(((unsigned)b) << 16); }
; template <int PASS>
; __device__ void lru_items(const Params& p, unsigned char* shm, int l) {
;     ...
;         { const int j = tid & 63;
; #pragma unroll
;           for (int i = 0; i < 8; ++i) { const int t = (tid >> 6) + 8 * i;
;               const float v = cb + bf2f(xraw[t * 64 + j]) * c0 + bf2f(xraw[(t + 1) * 64 + j]) * c1 + bf2f(xraw[(t + 2) * 64 + j]) * c2 + bf2f(xraw[(t + 3) * 64 + j]) * c3;
;               xcf[t * 65 + j] = v; xcb[t * 72 + j] = f2bf(v); } }
;         __syncthreads();
.LBB0_214:
	ds_read_u16 v0, v56
	ds_read_u16 v14, v57 offset:128
	ds_read_u16 v15, v57 offset:256
	ds_read_u16 v16, v57 offset:384
	s_mov_b32 s0, 0xf800000
	s_waitcnt lgkmcnt(3)
	v_lshlrev_b32_e32 v0, 16, v0
	s_waitcnt lgkmcnt(2)
	v_lshlrev_b32_e32 v14, 16, v14
	v_fma_f32 v0, v151, v0, v150
	v_fmac_f32_e32 v0, v154, v14
	s_waitcnt lgkmcnt(1)
	v_lshlrev_b32_e32 v14, 16, v15
	v_fmac_f32_e32 v0, v153, v14
	s_waitcnt lgkmcnt(0)
	v_lshlrev_b32_e32 v14, 16, v16
	v_fmac_f32_e32 v0, v152, v14
	v_cvt_pk_bf16_f32 v14, v0, v1
	ds_write_b16 v148, v14 offset:25344
	ds_read_u16 v14, v58
	ds_write_b32 v147, v0 offset:8704
	ds_read_u16 v0, v59 offset:128
	ds_read_u16 v15, v59 offset:256
	ds_read_u16 v16, v59 offset:384
	s_waitcnt lgkmcnt(4)
	v_lshlrev_b32_e32 v14, 16, v14
	v_fma_f32 v14, v151, v14, v150
	s_waitcnt lgkmcnt(2)
	v_lshlrev_b32_e32 v0, 16, v0
	v_fmac_f32_e32 v14, v154, v0
	s_waitcnt lgkmcnt(1)
	v_lshlrev_b32_e32 v0, 16, v15
	v_fmac_f32_e32 v14, v153, v0
	s_waitcnt lgkmcnt(0)
	v_lshlrev_b32_e32 v0, 16, v16
	v_fmac_f32_e32 v14, v152, v0
	v_cvt_pk_bf16_f32 v0, v14, v1
	ds_write_b16 v148, v0 offset:26496
	ds_read_u16 v0, v60
	ds_write_b32 v147, v14 offset:10784
	ds_read_u16 v14, v61 offset:128
	ds_read_u16 v15, v61 offset:256
	ds_read_u16 v16, v61 offset:384
	s_waitcnt lgkmcnt(4)
	v_lshlrev_b32_e32 v0, 16, v0
	v_fma_f32 v0, v151, v0, v150
	s_waitcnt lgkmcnt(2)
	v_lshlrev_b32_e32 v14, 16, v14
	v_fmac_f32_e32 v0, v154, v14
	s_waitcnt lgkmcnt(1)
	v_lshlrev_b32_e32 v14, 16, v15
	v_fmac_f32_e32 v0, v153, v14
	s_waitcnt lgkmcnt(0)
	v_lshlrev_b32_e32 v14, 16, v16
	v_fmac_f32_e32 v0, v152, v14
	v_cvt_pk_bf16_f32 v14, v0, v1
	ds_write_b16 v148, v14 offset:27648
	ds_read_u16 v14, v62
	ds_write_b32 v147, v0 offset:12864
	ds_read_u16 v0, v63 offset:128
	ds_read_u16 v15, v63 offset:256
	ds_read_u16 v16, v63 offset:384
	s_waitcnt lgkmcnt(4)
	v_lshlrev_b32_e32 v14, 16, v14
	v_fma_f32 v14, v151, v14, v150
	s_waitcnt lgkmcnt(2)
	v_lshlrev_b32_e32 v0, 16, v0
	v_fmac_f32_e32 v14, v154, v0
	s_waitcnt lgkmcnt(1)
	v_lshlrev_b32_e32 v0, 16, v15
	v_fmac_f32_e32 v14, v153, v0
	s_waitcnt lgkmcnt(0)
	v_lshlrev_b32_e32 v0, 16, v16
	v_fmac_f32_e32 v14, v152, v0
	v_cvt_pk_bf16_f32 v0, v14, v1
	ds_write_b16 v148, v0 offset:28800
	ds_read_u16 v0, v64
	ds_write_b32 v147, v14 offset:14944
	ds_read_u16 v14, v65 offset:128
	ds_read_u16 v15, v65 offset:256
	ds_read_u16 v16, v65 offset:384
	s_waitcnt lgkmcnt(4)
	v_lshlrev_b32_e32 v0, 16, v0
	v_fma_f32 v0, v151, v0, v150
	s_waitcnt lgkmcnt(2)
	v_lshlrev_b32_e32 v14, 16, v14
	v_fmac_f32_e32 v0, v154, v14
	s_waitcnt lgkmcnt(1)
	v_lshlrev_b32_e32 v14, 16, v15
	v_fmac_f32_e32 v0, v153, v14
	s_waitcnt lgkmcnt(0)
	v_lshlrev_b32_e32 v14, 16, v16
	v_fmac_f32_e32 v0, v152, v14
	v_cvt_pk_bf16_f32 v14, v0, v1
	ds_write_b16 v148, v14 offset:29952
	ds_read_u16 v14, v66
	ds_write_b32 v147, v0 offset:17024
	ds_read_u16 v0, v67 offset:128
	ds_read_u16 v15, v67 offset:256
	ds_read_u16 v16, v67 offset:384
	s_waitcnt lgkmcnt(4)
	v_lshlrev_b32_e32 v14, 16, v14
	v_fma_f32 v14, v151, v14, v150
	s_waitcnt lgkmcnt(2)
	v_lshlrev_b32_e32 v0, 16, v0
	v_fmac_f32_e32 v14, v154, v0
	s_waitcnt lgkmcnt(1)
	v_lshlrev_b32_e32 v0, 16, v15
	v_fmac_f32_e32 v14, v153, v0
	s_waitcnt lgkmcnt(0)
	v_lshlrev_b32_e32 v0, 16, v16
	v_fmac_f32_e32 v14, v152, v0
	v_cvt_pk_bf16_f32 v0, v14, v1
	ds_write_b16 v148, v0 offset:31104
	ds_read_u16 v0, v68
	ds_write_b32 v147, v14 offset:19104
	ds_read_u16 v14, v69 offset:128
	ds_read_u16 v15, v69 offset:256
	ds_read_u16 v16, v69 offset:384
	s_waitcnt lgkmcnt(4)
	v_lshlrev_b32_e32 v0, 16, v0
	v_fma_f32 v0, v151, v0, v150
	s_waitcnt lgkmcnt(2)
	v_lshlrev_b32_e32 v14, 16, v14
	v_fmac_f32_e32 v0, v154, v14
	s_waitcnt lgkmcnt(1)
	v_lshlrev_b32_e32 v14, 16, v15
	v_fmac_f32_e32 v0, v153, v14
	s_waitcnt lgkmcnt(0)
	v_lshlrev_b32_e32 v14, 16, v16
	v_fmac_f32_e32 v0, v152, v14
	v_cvt_pk_bf16_f32 v14, v0, v1
	ds_write_b16 v148, v14 offset:32256
	ds_read_u16 v14, v70
	ds_write_b32 v147, v0 offset:21184
	ds_read_u16 v0, v71 offset:128
	ds_read_u16 v15, v71 offset:256
	ds_read_u16 v16, v71 offset:384
	s_waitcnt lgkmcnt(4)
	v_lshlrev_b32_e32 v14, 16, v14
	v_fma_f32 v14, v151, v14, v150
	s_waitcnt lgkmcnt(2)
	v_lshlrev_b32_e32 v0, 16, v0
	v_fmac_f32_e32 v14, v154, v0
	s_waitcnt lgkmcnt(1)
	v_lshlrev_b32_e32 v0, 16, v15
	v_fmac_f32_e32 v14, v153, v0
	s_waitcnt lgkmcnt(0)
	v_lshlrev_b32_e32 v0, 16, v16
	v_fmac_f32_e32 v14, v152, v0
	ds_write_b32 v147, v14 offset:23264
	v_cvt_pk_bf16_f32 v0, v14, v1
	ds_write_b16 v148, v0 offset:33408
	s_waitcnt lgkmcnt(0)
	s_barrier
; __device__ __forceinline__ float sigm(float x) { return __builtin_amdgcn_rcpf(1.0f + __expf(-x)); }
; template <int PASS>
; __device__ void lru_items(const Params& p, unsigned char* shm, int l) {
;     ...
;         { const int d = w >> 2, tt = w & 3;
;           const bf16x8 a0 = *(const bf16x8*)(xcb + (tt * 16 + fr) * 72 + fq * 8), a1 = *(const bf16x8*)(xcb + (tt * 16 + fr) * 72 + 32 + fq * 8);
; #pragma unroll
;           for (int jt = 0; jt < 4; ++jt) {
;               f32x4 accr = (f32x4){0.f, 0.f, 0.f, 0.f}, acci = (f32x4){0.f, 0.f, 0.f, 0.f};
;               const bf16_t* wr_ = wt + ((d * 2 + 0) * 64 + jt * 16 + fr) * 72 + fq * 8; const bf16_t* wi_ = wt + ((d * 2 + 1) * 64 + jt * 16 + fr) * 72 + fq * 8;
;               accr = __builtin_amdgcn_mfma_f32_16x16x32_bf16(a0, *(const bf16x8*)wr_, accr, 0, 0, 0);
;               accr = __builtin_amdgcn_mfma_f32_16x16x32_bf16(a1, *(const bf16x8*)(wr_ + 32), accr, 0, 0, 0);
;               acci = __builtin_amdgcn_mfma_f32_16x16x32_bf16(a0, *(const bf16x8*)wi_, acci, 0, 0, 0);
;               acci = __builtin_amdgcn_mfma_f32_16x16x32_bf16(a1, *(const bf16x8*)(wi_ + 32), acci, 0, 0, 0);
;               const int j = jt * 16 + fr;
; #pragma unroll
;               for (int i = 0; i < 4; ++i) { const int t = tt * 16 + fq * 4 + i;
;                   const float r = sigm(accr[i] + gba[jt]), ig = sigm(acci[i] + gbx[jt]), a = __expf(r * gsp[jt]);
;                   As[(d * 64 + t) * 64 + j] = a;
;                   Bs[(d * 64 + t) * 64 + j] = sqrtf(fmaxf(1.0f - a * a, 0.f)) * ig * xcf[t * 65 + j]; }
;           } }
	ds_read_b128 v[18:21], v47 offset:25344
	ds_read_b128 v[14:17], v47 offset:25408
	ds_read_b128 v[160:163], v72 offset:34560
	ds_read_b128 v[164:167], v72 offset:34624
	s_waitcnt lgkmcnt(1)
	v_mfma_f32_16x16x32_bf16 v[160:163], v[18:21], v[160:163], 0
	ds_read_b128 v[168:171], v73 offset:43840
	s_waitcnt lgkmcnt(1)
	v_mfma_f32_16x16x32_bf16 v[160:163], v[14:17], v[164:167], v[160:163]
	ds_read_b128 v[164:167], v73 offset:43776
	s_waitcnt lgkmcnt(0)
	v_mfma_f32_16x16x32_bf16 v[164:167], v[18:21], v[164:167], 0
	s_waitcnt vmcnt(9)
	s_nop 3
	v_add_f32_e32 v0, v157, v160
	v_mul_f32_e32 v0, 0xbfb8aa3b, v0
	v_exp_f32_e32 v0, v0
	v_mfma_f32_16x16x32_bf16 v[164:167], v[14:17], v[168:171], v[164:167]
	v_add_f32_e32 v0, 1.0, v0
	v_rcp_f32_e32 v0, v0
	s_nop 0
	v_mul_f32_e32 v0, v23, v0
	v_mul_f32_e32 v0, 0x3fb8aa3b, v0
	v_exp_f32_e32 v0, v0
	s_waitcnt vmcnt(5)
	s_nop 0
	v_add_f32_e32 v35, v155, v164
	v_mul_f32_e32 v35, 0xbfb8aa3b, v35
	v_exp_f32_e32 v35, v35
	v_fma_f32 v36, -v0, v0, 1.0
	v_max_f32_e32 v36, 0, v36
	ds_write_b32 v74, v0
	v_add_f32_e32 v35, 1.0, v35
	v_sqrt_f32_e32 v37, v36
	v_rcp_f32_e32 v35, v35
	v_mov_b32_e32 v0, v37
	s_nop 0
	s_nop 1
	v_add_f32_e32 v37, v157, v161
	v_mul_f32_e32 v37, 0xbfb8aa3b, v37
	v_exp_f32_e32 v37, v37
	ds_read_b32 v159, v149 offset:8704
	s_nop 1
	v_add_f32_e32 v36, 1.0, v37
	v_rcp_f32_e32 v36, v36
	v_mul_f32_e32 v0, v35, v0
	s_waitcnt lgkmcnt(0)
	v_mul_f32_e32 v0, v159, v0
	ds_write_b32 v75, v0
	v_mul_f32_e32 v0, v23, v36
	v_mul_f32_e32 v0, 0x3fb8aa3b, v0
	v_exp_f32_e32 v0, v0
	v_add_f32_e32 v35, v155, v165
	v_mul_f32_e32 v35, 0xbfb8aa3b, v35
	v_exp_f32_e32 v35, v35
	v_fma_f32 v36, -v0, v0, 1.0
	v_max_f32_e32 v36, 0, v36
	ds_write_b32 v76, v0
	v_add_f32_e32 v35, 1.0, v35
	v_sqrt_f32_e32 v37, v36
	v_rcp_f32_e32 v35, v35
	v_mov_b32_e32 v0, v37
	s_nop 0
	s_nop 1
	v_add_f32_e32 v37, v157, v162
	v_mul_f32_e32 v37, 0xbfb8aa3b, v37
	v_exp_f32_e32 v37, v37
	ds_read_b32 v159, v149 offset:8964
	s_nop 1
	v_add_f32_e32 v36, 1.0, v37
	v_rcp_f32_e32 v36, v36
	v_mul_f32_e32 v0, v35, v0
	s_waitcnt lgkmcnt(0)
	v_mul_f32_e32 v0, v159, v0
	ds_write_b32 v77, v0
	v_mul_f32_e32 v0, v23, v36
	v_mul_f32_e32 v0, 0x3fb8aa3b, v0
	v_exp_f32_e32 v0, v0
	v_add_f32_e32 v35, v155, v166
	v_mul_f32_e32 v35, 0xbfb8aa3b, v35
	v_exp_f32_e32 v35, v35
	v_fma_f32 v36, -v0, v0, 1.0
	v_max_f32_e32 v36, 0, v36
	ds_write_b32 v78, v0
	v_add_f32_e32 v35, 1.0, v35
	v_sqrt_f32_e32 v37, v36
	v_rcp_f32_e32 v35, v35
	v_mov_b32_e32 v0, v37
	s_nop 0
	s_nop 1
	v_add_f32_e32 v37, v157, v163
	v_mul_f32_e32 v37, 0xbfb8aa3b, v37
	v_exp_f32_e32 v37, v37
	ds_read_b32 v159, v149 offset:9224
	s_nop 1
	v_add_f32_e32 v36, 1.0, v37
	v_rcp_f32_e32 v36, v36
	v_mul_f32_e32 v0, v35, v0
	s_waitcnt lgkmcnt(0)
	v_mul_f32_e32 v0, v159, v0
	ds_write_b32 v79, v0
	v_mul_f32_e32 v0, v23, v36
	v_mul_f32_e32 v0, 0x3fb8aa3b, v0
	v_exp_f32_e32 v0, v0
	v_add_f32_e32 v35, v155, v167
	v_mul_f32_e32 v35, 0xbfb8aa3b, v35
	v_exp_f32_e32 v35, v35
	v_fma_f32 v36, -v0, v0, 1.0
	v_max_f32_e32 v36, 0, v36
	ds_write_b32 v80, v0
	v_add_f32_e32 v35, 1.0, v35
	v_sqrt_f32_e32 v37, v36
	v_rcp_f32_e32 v35, v35
	v_mov_b32_e32 v0, v37
	s_nop 0
	s_nop 1
	ds_read_b32 v159, v149 offset:9484
	s_nop 1
	v_mul_f32_e32 v0, v35, v0
	s_waitcnt lgkmcnt(0)
	v_mul_f32_e32 v0, v0, v159
	ds_write_b32 v81, v0
	ds_read_b128 v[160:163], v72 offset:36864
	ds_read_b128 v[164:167], v72 offset:36928
	s_waitcnt lgkmcnt(1)
	v_mfma_f32_16x16x32_bf16 v[160:163], v[18:21], v[160:163], 0
	ds_read_b128 v[168:171], v73 offset:46144
	s_waitcnt lgkmcnt(1)
	v_mfma_f32_16x16x32_bf16 v[160:163], v[14:17], v[164:167], v[160:163]
	ds_read_b128 v[164:167], v73 offset:46080
	s_waitcnt lgkmcnt(0)
	v_mfma_f32_16x16x32_bf16 v[164:167], v[18:21], v[164:167], 0
	s_nop 4
	v_add_f32_e32 v0, v158, v160
	v_mul_f32_e32 v0, 0xbfb8aa3b, v0
	v_exp_f32_e32 v0, v0
	v_mfma_f32_16x16x32_bf16 v[164:167], v[14:17], v[168:171], v[164:167]
	v_add_f32_e32 v0, 1.0, v0
	v_rcp_f32_e32 v0, v0
	s_nop 0
	v_mul_f32_e32 v0, v22, v0
	v_mul_f32_e32 v0, 0x3fb8aa3b, v0
	v_exp_f32_e32 v0, v0
	s_waitcnt vmcnt(4)
	s_nop 0
	v_add_f32_e32 v35, v156, v164
	v_mul_f32_e32 v35, 0xbfb8aa3b, v35
	v_exp_f32_e32 v35, v35
	v_fma_f32 v36, -v0, v0, 1.0
	v_max_f32_e32 v36, 0, v36
	ds_write_b32 v82, v0
	v_add_f32_e32 v35, 1.0, v35
	v_sqrt_f32_e32 v37, v36
	v_rcp_f32_e32 v35, v35
	v_mov_b32_e32 v0, v37
	s_nop 0
	s_nop 1
	v_add_f32_e32 v37, v158, v161
	v_mul_f32_e32 v37, 0xbfb8aa3b, v37
	v_exp_f32_e32 v37, v37
	ds_read_b32 v159, v149 offset:8768
	s_nop 1
	v_add_f32_e32 v36, 1.0, v37
	v_rcp_f32_e32 v36, v36
	v_mul_f32_e32 v0, v35, v0
	s_waitcnt lgkmcnt(0)
	v_mul_f32_e32 v0, v159, v0
	ds_write_b32 v83, v0
	v_mul_f32_e32 v0, v22, v36
	v_mul_f32_e32 v0, 0x3fb8aa3b, v0
	v_exp_f32_e32 v0, v0
	v_add_f32_e32 v35, v156, v165
	v_mul_f32_e32 v35, 0xbfb8aa3b, v35
	v_exp_f32_e32 v35, v35
	v_fma_f32 v36, -v0, v0, 1.0
	v_max_f32_e32 v36, 0, v36
	ds_write_b32 v84, v0
	v_add_f32_e32 v35, 1.0, v35
	v_sqrt_f32_e32 v37, v36
	v_rcp_f32_e32 v35, v35
	v_mov_b32_e32 v0, v37
	s_nop 0
	s_nop 1
	v_add_f32_e32 v37, v158, v162
	v_mul_f32_e32 v37, 0xbfb8aa3b, v37
	v_exp_f32_e32 v37, v37
	ds_read_b32 v159, v149 offset:9028
	s_nop 1
	v_add_f32_e32 v36, 1.0, v37
	v_rcp_f32_e32 v36, v36
	v_mul_f32_e32 v0, v35, v0
	s_waitcnt lgkmcnt(0)
	v_mul_f32_e32 v0, v159, v0
	ds_write_b32 v85, v0
	v_mul_f32_e32 v0, v22, v36
	v_mul_f32_e32 v0, 0x3fb8aa3b, v0
	v_exp_f32_e32 v0, v0
	v_add_f32_e32 v35, v156, v166
	v_mul_f32_e32 v35, 0xbfb8aa3b, v35
	v_exp_f32_e32 v35, v35
	v_fma_f32 v36, -v0, v0, 1.0
	v_max_f32_e32 v36, 0, v36
	ds_write_b32 v86, v0
	v_add_f32_e32 v35, 1.0, v35
	v_sqrt_f32_e32 v37, v36
	v_rcp_f32_e32 v35, v35
	v_mov_b32_e32 v0, v37
	s_nop 0
	s_nop 1
	v_add_f32_e32 v37, v158, v163
	v_mul_f32_e32 v37, 0xbfb8aa3b, v37
	v_exp_f32_e32 v37, v37
	ds_read_b32 v159, v149 offset:9288
	s_nop 1
	v_add_f32_e32 v36, 1.0, v37
	v_rcp_f32_e32 v36, v36
	v_mul_f32_e32 v0, v35, v0
	s_waitcnt lgkmcnt(0)
; __device__ __forceinline__ float sigm(float x) { return __builtin_amdgcn_rcpf(1.0f + __expf(-x)); }
; template <int PASS>
; __device__ void lru_items(const Params& p, unsigned char* shm, int l) {
;     ...
;           for (int jt = 0; jt < 4; ++jt) {
;               f32x4 accr = (f32x4){0.f, 0.f, 0.f, 0.f}, acci = (f32x4){0.f, 0.f, 0.f, 0.f};
;               const bf16_t* wr_ = wt + ((d * 2 + 0) * 64 + jt * 16 + fr) * 72 + fq * 8; const bf16_t* wi_ = wt + ((d * 2 + 1) * 64 + jt * 16 + fr) * 72 + fq * 8;
;               accr = __builtin_amdgcn_mfma_f32_16x16x32_bf16(a0, *(const bf16x8*)wr_, accr, 0, 0, 0);
;               accr = __builtin_amdgcn_mfma_f32_16x16x32_bf16(a1, *(const bf16x8*)(wr_ + 32), accr, 0, 0, 0);
;               acci = __builtin_amdgcn_mfma_f32_16x16x32_bf16(a0, *(const bf16x8*)wi_, acci, 0, 0, 0);
;               acci = __builtin_amdgcn_mfma_f32_16x16x32_bf16(a1, *(const bf16x8*)(wi_ + 32), acci, 0, 0, 0);
;               const int j = jt * 16 + fr;
; #pragma unroll
;               for (int i = 0; i < 4; ++i) { const int t = tt * 16 + fq * 4 + i;
;                   const float r = sigm(accr[i] + gba[jt]), ig = sigm(acci[i] + gbx[jt]), a = __expf(r * gsp[jt]);
;                   As[(d * 64 + t) * 64 + j] = a;
;                   Bs[(d * 64 + t) * 64 + j] = sqrtf(fmaxf(1.0f - a * a, 0.f)) * ig * xcf[t * 65 + j]; }
;           } }
	v_mul_f32_e32 v0, v159, v0
	ds_write_b32 v87, v0
	v_mul_f32_e32 v0, v22, v36
	v_mul_f32_e32 v0, 0x3fb8aa3b, v0
	v_exp_f32_e32 v0, v0
	v_add_f32_e32 v35, v156, v167
	v_mul_f32_e32 v35, 0xbfb8aa3b, v35
	v_exp_f32_e32 v35, v35
	v_fma_f32 v36, -v0, v0, 1.0
	v_max_f32_e32 v36, 0, v36
	ds_write_b32 v88, v0
	v_add_f32_e32 v35, 1.0, v35
	v_sqrt_f32_e32 v37, v36
	v_rcp_f32_e32 v35, v35
	v_mov_b32_e32 v0, v37
	s_nop 0
	s_nop 1
	ds_read_b32 v159, v149 offset:9548
	s_nop 1
	v_mul_f32_e32 v0, v35, v0
	s_waitcnt lgkmcnt(0)
	v_mul_f32_e32 v0, v0, v159
	ds_write_b32 v89, v0
	ds_read_b128 v[160:163], v72 offset:39168
	ds_read_b128 v[164:167], v72 offset:39232
	s_waitcnt lgkmcnt(1)
	v_mfma_f32_16x16x32_bf16 v[160:163], v[18:21], v[160:163], 0
	ds_read_b128 v[168:171], v73 offset:48448
	s_waitcnt lgkmcnt(1)
	v_mfma_f32_16x16x32_bf16 v[160:163], v[14:17], v[164:167], v[160:163]
	ds_read_b128 v[164:167], v73 offset:48384
	s_waitcnt lgkmcnt(0)
	v_mfma_f32_16x16x32_bf16 v[164:167], v[18:21], v[164:167], 0
	s_nop 4
	v_add_f32_e32 v0, v40, v160
	v_mul_f32_e32 v0, 0xbfb8aa3b, v0
	v_exp_f32_e32 v0, v0
	v_mfma_f32_16x16x32_bf16 v[164:167], v[14:17], v[168:171], v[164:167]
	v_add_f32_e32 v0, 1.0, v0
	v_rcp_f32_e32 v0, v0
	s_nop 0
	v_mul_f32_e32 v0, v25, v0
	v_mul_f32_e32 v0, 0x3fb8aa3b, v0
	v_exp_f32_e32 v0, v0
	s_waitcnt vmcnt(3)
	s_nop 0
	v_add_f32_e32 v35, v38, v164
	v_mul_f32_e32 v35, 0xbfb8aa3b, v35
	v_exp_f32_e32 v35, v35
	v_fma_f32 v36, -v0, v0, 1.0
	v_max_f32_e32 v36, 0, v36
	ds_write_b32 v90, v0
	v_add_f32_e32 v35, 1.0, v35
	v_sqrt_f32_e32 v37, v36
	v_rcp_f32_e32 v35, v35
	v_mov_b32_e32 v0, v37
	s_nop 0
	s_nop 1
	v_add_f32_e32 v37, v40, v161
	v_mul_f32_e32 v37, 0xbfb8aa3b, v37
	v_exp_f32_e32 v37, v37
	ds_read_b32 v159, v149 offset:8832
	s_nop 1
	v_add_f32_e32 v36, 1.0, v37
	v_rcp_f32_e32 v36, v36
	v_mul_f32_e32 v0, v35, v0
	s_waitcnt lgkmcnt(0)
	v_mul_f32_e32 v0, v159, v0
	ds_write_b32 v91, v0
	v_mul_f32_e32 v0, v25, v36
	v_mul_f32_e32 v0, 0x3fb8aa3b, v0
	v_exp_f32_e32 v0, v0
	v_add_f32_e32 v35, v38, v165
	v_mul_f32_e32 v35, 0xbfb8aa3b, v35
	v_exp_f32_e32 v35, v35
	v_fma_f32 v36, -v0, v0, 1.0
	v_max_f32_e32 v36, 0, v36
	ds_write_b32 v92, v0
	v_add_f32_e32 v35, 1.0, v35
	v_sqrt_f32_e32 v37, v36
	v_rcp_f32_e32 v35, v35
	v_mov_b32_e32 v0, v37
	s_nop 0
	s_nop 1
	v_add_f32_e32 v37, v40, v162
	v_mul_f32_e32 v37, 0xbfb8aa3b, v37
	v_exp_f32_e32 v37, v37
	ds_read_b32 v159, v149 offset:9092
	s_nop 1
	v_add_f32_e32 v36, 1.0, v37
	v_rcp_f32_e32 v36, v36
	v_mul_f32_e32 v0, v35, v0
	s_waitcnt lgkmcnt(0)
	v_mul_f32_e32 v0, v159, v0
	ds_write_b32 v93, v0
	v_mul_f32_e32 v0, v25, v36
	v_mul_f32_e32 v0, 0x3fb8aa3b, v0
	v_exp_f32_e32 v0, v0
	v_add_f32_e32 v35, v38, v166
	v_mul_f32_e32 v35, 0xbfb8aa3b, v35
	v_exp_f32_e32 v35, v35
	v_fma_f32 v36, -v0, v0, 1.0
	v_max_f32_e32 v36, 0, v36
	ds_write_b32 v94, v0
	v_add_f32_e32 v35, 1.0, v35
	v_sqrt_f32_e32 v37, v36
	v_rcp_f32_e32 v35, v35
	v_mov_b32_e32 v0, v37
	s_nop 0
	s_nop 1
	v_add_f32_e32 v37, v40, v163
	v_mul_f32_e32 v37, 0xbfb8aa3b, v37
	v_exp_f32_e32 v37, v37
	ds_read_b32 v159, v149 offset:9352
	s_nop 1
	v_add_f32_e32 v36, 1.0, v37
	v_rcp_f32_e32 v36, v36
	v_mul_f32_e32 v0, v35, v0
	s_waitcnt lgkmcnt(0)
	v_mul_f32_e32 v0, v159, v0
	ds_write_b32 v95, v0
	v_mul_f32_e32 v0, v25, v36
	v_mul_f32_e32 v0, 0x3fb8aa3b, v0
	v_exp_f32_e32 v0, v0
	v_add_f32_e32 v35, v38, v167
	v_mul_f32_e32 v35, 0xbfb8aa3b, v35
	v_exp_f32_e32 v35, v35
	v_fma_f32 v36, -v0, v0, 1.0
	v_max_f32_e32 v36, 0, v36
	ds_write_b32 v96, v0
	v_add_f32_e32 v35, 1.0, v35
	v_sqrt_f32_e32 v37, v36
	v_rcp_f32_e32 v35, v35
	v_mov_b32_e32 v0, v37
	s_nop 0
	s_nop 1
	ds_read_b32 v159, v149 offset:9612
	s_nop 1
	v_mul_f32_e32 v0, v35, v0
	s_waitcnt lgkmcnt(0)
	v_mul_f32_e32 v0, v0, v159
	ds_write_b32 v97, v0
	ds_read_b128 v[160:163], v72 offset:41472
	ds_read_b128 v[164:167], v72 offset:41536
	s_waitcnt lgkmcnt(1)
	v_mfma_f32_16x16x32_bf16 v[160:163], v[18:21], v[160:163], 0
	ds_read_b128 v[168:171], v73 offset:50752
	s_waitcnt lgkmcnt(1)
	v_mfma_f32_16x16x32_bf16 v[160:163], v[14:17], v[164:167], v[160:163]
	ds_read_b128 v[164:167], v73 offset:50688
	s_waitcnt lgkmcnt(0)
	v_mfma_f32_16x16x32_bf16 v[18:21], v[18:21], v[164:167], 0
	s_nop 4
	v_add_f32_e32 v0, v41, v160
	v_mul_f32_e32 v0, 0xbfb8aa3b, v0
	v_exp_f32_e32 v0, v0
	v_mfma_f32_16x16x32_bf16 v[14:17], v[14:17], v[168:171], v[18:21]
	v_add_f32_e32 v0, 1.0, v0
	v_rcp_f32_e32 v0, v0
	s_nop 0
	v_mul_f32_e32 v0, v24, v0
	v_mul_f32_e32 v0, 0x3fb8aa3b, v0
	v_exp_f32_e32 v0, v0
	s_waitcnt vmcnt(2)
	s_nop 0
	v_add_f32_e32 v14, v39, v14
	v_mul_f32_e32 v14, 0xbfb8aa3b, v14
	v_exp_f32_e32 v14, v14
	v_fma_f32 v18, -v0, v0, 1.0
	v_max_f32_e32 v18, 0, v18
	ds_write_b32 v98, v0
	v_add_f32_e32 v14, 1.0, v14
	v_sqrt_f32_e32 v19, v18
	v_rcp_f32_e32 v14, v14
	v_mov_b32_e32 v0, v19
	s_nop 0
	s_nop 1
	v_add_f32_e32 v19, v41, v161
	v_mul_f32_e32 v19, 0xbfb8aa3b, v19
	v_exp_f32_e32 v19, v19
	ds_read_b32 v20, v149 offset:8896
	s_nop 1
	v_add_f32_e32 v18, 1.0, v19
	v_rcp_f32_e32 v18, v18
	v_mul_f32_e32 v0, v14, v0
	s_waitcnt lgkmcnt(0)
	v_mul_f32_e32 v0, v20, v0
	ds_write_b32 v99, v0
	v_mul_f32_e32 v0, v24, v18
	v_mul_f32_e32 v0, 0x3fb8aa3b, v0
	v_exp_f32_e32 v0, v0
	v_add_f32_e32 v14, v39, v15
	v_mul_f32_e32 v14, 0xbfb8aa3b, v14
	v_exp_f32_e32 v14, v14
	v_fma_f32 v15, -v0, v0, 1.0
	v_max_f32_e32 v15, 0, v15
	ds_write_b32 v100, v0
	v_add_f32_e32 v14, 1.0, v14
	v_sqrt_f32_e32 v18, v15
	v_rcp_f32_e32 v14, v14
	v_mov_b32_e32 v0, v18
	s_nop 0
	s_nop 1
	v_add_f32_e32 v18, v41, v162
	v_mul_f32_e32 v18, 0xbfb8aa3b, v18
	v_exp_f32_e32 v18, v18
	ds_read_b32 v19, v149 offset:9156
	s_nop 1
	v_add_f32_e32 v15, 1.0, v18
	v_rcp_f32_e32 v15, v15
	v_mul_f32_e32 v0, v14, v0
	s_waitcnt lgkmcnt(0)
	v_mul_f32_e32 v0, v19, v0
	ds_write_b32 v101, v0
	v_mul_f32_e32 v0, v24, v15
	v_mul_f32_e32 v0, 0x3fb8aa3b, v0
	v_exp_f32_e32 v0, v0
	v_add_f32_e32 v14, v39, v16
	v_mul_f32_e32 v14, 0xbfb8aa3b, v14
	v_exp_f32_e32 v14, v14
	v_fma_f32 v15, -v0, v0, 1.0
	v_max_f32_e32 v15, 0, v15
	ds_write_b32 v102, v0
	v_add_f32_e32 v14, 1.0, v14
	v_sqrt_f32_e32 v16, v15
	v_rcp_f32_e32 v14, v14
	v_mov_b32_e32 v0, v16
	s_nop 0
	s_nop 1
	v_add_f32_e32 v16, v41, v163
	v_mul_f32_e32 v16, 0xbfb8aa3b, v16
	v_exp_f32_e32 v16, v16
	ds_read_b32 v18, v149 offset:9416
	s_nop 1
	v_add_f32_e32 v15, 1.0, v16
	v_rcp_f32_e32 v15, v15
	v_mul_f32_e32 v0, v14, v0
	s_waitcnt lgkmcnt(0)
	v_mul_f32_e32 v0, v18, v0
	ds_write_b32 v103, v0
	v_mul_f32_e32 v0, v24, v15
	v_mul_f32_e32 v0, 0x3fb8aa3b, v0
	v_exp_f32_e32 v0, v0
	v_add_f32_e32 v14, v39, v17
	v_mul_f32_e32 v14, 0xbfb8aa3b, v14
	v_exp_f32_e32 v14, v14
	v_fma_f32 v15, -v0, v0, 1.0
	v_max_f32_e32 v15, 0, v15
	ds_write_b32 v104, v0
	v_add_f32_e32 v14, 1.0, v14
	v_sqrt_f32_e32 v16, v15
	v_rcp_f32_e32 v14, v14
	v_mov_b32_e32 v0, v16
	s_nop 0
	s_nop 1
	ds_read_b32 v17, v149 offset:9676
	s_nop 1
	v_mul_f32_e32 v0, v14, v0
	s_waitcnt lgkmcnt(0)
	v_mul_f32_e32 v0, v0, v17
	ds_write_b32 v105, v0
	s_waitcnt lgkmcnt(0)
	s_barrier
; template <int PASS>
; __device__ void lru_items(const Params& p, unsigned char* shm, int l) {
;     ...
;         {
;             const int seg = tid >> 7, d = (tid >> 6) & 1, j = tid & 63;
;             float h = 0.f, P = 1.f;
; #pragma unroll
;             for (int s = 0; s < 16; ++s) { const int st = seg * 16 + s, t = d ? 63 - st : st; const float a = As[(d * 64 + t) * 64 + j]; h = a * h + Bs[(d * 64 + t) * 64 + j]; P *= a; }
;             Pq[seg * 128 + (tid & 127)] = P; Hq[seg * 128 + (tid & 127)] = h;
;             __syncthreads();
;     ...
;                 float c = cin;
; #pragma unroll
;                 for (int q = 0; q < 3; ++q) if (q < seg) c = Pq[q * 128 + (tid & 127)] * c + Hq[q * 128 + (tid & 127)];
	ds_read_b32 v0, v51
	ds_read_b32 v14, v106
	ds_read_b32 v15, v107
	ds_read_b32 v16, v108
	ds_read_b32 v17, v109
	ds_read_b32 v18, v110
	ds_read_b32 v19, v111
	ds_read_b32 v20, v112
	s_waitcnt lgkmcnt(6)
	v_fmac_f32_e32 v14, 0, v0
	s_waitcnt lgkmcnt(4)
	v_fmac_f32_e32 v16, v14, v15
	v_mul_f32_e32 v0, v0, v15
	s_waitcnt lgkmcnt(2)
	v_fmac_f32_e32 v18, v16, v17
	v_mul_f32_e32 v0, v0, v17
	s_waitcnt lgkmcnt(0)
	v_fmac_f32_e32 v20, v18, v19
	v_mul_f32_e32 v0, v0, v19
	ds_read_b32 v14, v113
	ds_read_b32 v15, v114
	ds_read_b32 v16, v115
	ds_read_b32 v17, v116
	ds_read_b32 v18, v117
	ds_read_b32 v19, v118
	ds_read_b32 v21, v119
	ds_read_b32 v35, v120
	s_waitcnt lgkmcnt(6)
	v_fmac_f32_e32 v15, v20, v14
	v_mul_f32_e32 v0, v0, v14
	s_waitcnt lgkmcnt(4)
	v_fmac_f32_e32 v17, v15, v16
	v_mul_f32_e32 v0, v0, v16
	s_waitcnt lgkmcnt(2)
	v_fmac_f32_e32 v19, v17, v18
	v_mul_f32_e32 v0, v0, v18
	s_waitcnt lgkmcnt(0)
	v_fmac_f32_e32 v35, v19, v21
	v_mul_f32_e32 v0, v0, v21
	ds_read_b32 v14, v121
	ds_read_b32 v15, v122
	ds_read_b32 v16, v123
	ds_read_b32 v17, v124
	ds_read_b32 v18, v125
	ds_read_b32 v19, v126
	ds_read_b32 v20, v127
	ds_read_b32 v21, v128
	s_waitcnt lgkmcnt(6)
	v_fmac_f32_e32 v15, v35, v14
	v_mul_f32_e32 v0, v0, v14
	s_waitcnt lgkmcnt(4)
	v_fmac_f32_e32 v17, v15, v16
	v_mul_f32_e32 v0, v0, v16
	s_waitcnt lgkmcnt(2)
	v_fmac_f32_e32 v19, v17, v18
	v_mul_f32_e32 v0, v0, v18
	s_waitcnt lgkmcnt(0)
	v_fmac_f32_e32 v21, v19, v20
	v_mul_f32_e32 v0, v0, v20
	ds_read_b32 v14, v129
	ds_read_b32 v15, v130
	ds_read_b32 v16, v131
	ds_read_b32 v17, v132
	ds_read_b32 v18, v133
	ds_read_b32 v19, v134
	ds_read_b32 v20, v135
	ds_read_b32 v35, v136
	s_waitcnt lgkmcnt(7)
	v_mul_f32_e32 v0, v0, v14
	s_waitcnt lgkmcnt(6)
	v_fmac_f32_e32 v15, v21, v14
	s_waitcnt lgkmcnt(5)
	v_mul_f32_e32 v0, v0, v16
	s_waitcnt lgkmcnt(4)
	v_fmac_f32_e32 v17, v15, v16
	s_waitcnt lgkmcnt(3)
	v_mul_f32_e32 v0, v0, v18
	s_waitcnt lgkmcnt(2)
	v_fmac_f32_e32 v19, v17, v18
	s_waitcnt lgkmcnt(1)
	v_mul_f32_e32 v0, v0, v20
	s_waitcnt lgkmcnt(0)
	v_fmac_f32_e32 v35, v19, v20
	ds_write_b32 v48, v0
	ds_write_b32 v49, v35
	s_waitcnt lgkmcnt(0)
	s_barrier
	s_and_saveexec_b64 s[0:1], s[38:39]
	s_cbranch_execnz .LBB0_217
	s_or_b64 exec, exec, s[0:1]
	s_and_saveexec_b64 s[0:1], s[40:41]
	s_cbranch_execnz .LBB0_218

; __device__ __forceinline__ bf16_t f2bf(float f) { return (bf16_t)(cvt_pk_bf16(f, 0.f) & 0xffffu); }
; __device__ __forceinline__ float bf2f(bf16_t b) { return __uint_as_float(((unsigned)b) << 16); }
; template <int PASS>
; __device__ void lru_items(const Params& p, unsigned char* shm, int l) {
;     ...
;         { const int j = tid & 63;
; #pragma unroll
;           for (int i = 0; i < 8; ++i) { const int t = (tid >> 6) + 8 * i;
;               const float v = cb + bf2f(xraw[t * 64 + j]) * c0 + bf2f(xraw[(t + 1) * 64 + j]) * c1 + bf2f(xraw[(t + 2) * 64 + j]) * c2 + bf2f(xraw[(t + 3) * 64 + j]) * c3;
;               xcf[t * 65 + j] = v; xcb[t * 72 + j] = f2bf(v); } }
;         __syncthreads();
.LBB0_310:
	ds_read_u16 v0, v51
	ds_read_u16 v10, v52 offset:128
	ds_read_u16 v11, v52 offset:256
	ds_read_u16 v12, v52 offset:384
	s_mov_b32 s0, 0xf800000
	s_waitcnt lgkmcnt(3)
	v_lshlrev_b32_e32 v0, 16, v0
	s_waitcnt lgkmcnt(2)
	v_lshlrev_b32_e32 v10, 16, v10
	v_fma_f32 v0, v149, v0, v148
	v_fmac_f32_e32 v0, v152, v10
	s_waitcnt lgkmcnt(1)
	v_lshlrev_b32_e32 v10, 16, v11
	v_fmac_f32_e32 v0, v151, v10
	s_waitcnt lgkmcnt(0)
	v_lshlrev_b32_e32 v10, 16, v12
	v_fmac_f32_e32 v0, v150, v10
	v_cvt_pk_bf16_f32 v10, v0, v1
	ds_write_b16 v146, v10 offset:25344
	ds_read_u16 v10, v53
	ds_write_b32 v145, v0 offset:8704
	ds_read_u16 v0, v54 offset:128
	ds_read_u16 v11, v54 offset:256
	ds_read_u16 v12, v54 offset:384
	s_waitcnt lgkmcnt(4)
	v_lshlrev_b32_e32 v10, 16, v10
	v_fma_f32 v10, v149, v10, v148
	s_waitcnt lgkmcnt(2)
	v_lshlrev_b32_e32 v0, 16, v0
	v_fmac_f32_e32 v10, v152, v0
	s_waitcnt lgkmcnt(1)
	v_lshlrev_b32_e32 v0, 16, v11
	v_fmac_f32_e32 v10, v151, v0
	s_waitcnt lgkmcnt(0)
	v_lshlrev_b32_e32 v0, 16, v12
	v_fmac_f32_e32 v10, v150, v0
	v_cvt_pk_bf16_f32 v0, v10, v1
	ds_write_b16 v146, v0 offset:26496
	ds_read_u16 v0, v55
	ds_write_b32 v145, v10 offset:10784
	ds_read_u16 v10, v56 offset:128
	ds_read_u16 v11, v56 offset:256
	ds_read_u16 v12, v56 offset:384
	s_waitcnt lgkmcnt(4)
	v_lshlrev_b32_e32 v0, 16, v0
	v_fma_f32 v0, v149, v0, v148
	s_waitcnt lgkmcnt(2)
	v_lshlrev_b32_e32 v10, 16, v10
	v_fmac_f32_e32 v0, v152, v10
	s_waitcnt lgkmcnt(1)
	v_lshlrev_b32_e32 v10, 16, v11
	v_fmac_f32_e32 v0, v151, v10
	s_waitcnt lgkmcnt(0)
	v_lshlrev_b32_e32 v10, 16, v12
	v_fmac_f32_e32 v0, v150, v10
	v_cvt_pk_bf16_f32 v10, v0, v1
	ds_write_b16 v146, v10 offset:27648
	ds_read_u16 v10, v57
	ds_write_b32 v145, v0 offset:12864
	ds_read_u16 v0, v58 offset:128
	ds_read_u16 v11, v58 offset:256
	ds_read_u16 v12, v58 offset:384
	s_waitcnt lgkmcnt(4)
	v_lshlrev_b32_e32 v10, 16, v10
	v_fma_f32 v10, v149, v10, v148
	s_waitcnt lgkmcnt(2)
	v_lshlrev_b32_e32 v0, 16, v0
	v_fmac_f32_e32 v10, v152, v0
	s_waitcnt lgkmcnt(1)
	v_lshlrev_b32_e32 v0, 16, v11
	v_fmac_f32_e32 v10, v151, v0
	s_waitcnt lgkmcnt(0)
	v_lshlrev_b32_e32 v0, 16, v12
	v_fmac_f32_e32 v10, v150, v0
	v_cvt_pk_bf16_f32 v0, v10, v1
	ds_write_b16 v146, v0 offset:28800
	ds_read_u16 v0, v59
	ds_write_b32 v145, v10 offset:14944
	ds_read_u16 v10, v60 offset:128
	ds_read_u16 v11, v60 offset:256
	ds_read_u16 v12, v60 offset:384
	s_waitcnt lgkmcnt(4)
	v_lshlrev_b32_e32 v0, 16, v0
	v_fma_f32 v0, v149, v0, v148
	s_waitcnt lgkmcnt(2)
	v_lshlrev_b32_e32 v10, 16, v10
	v_fmac_f32_e32 v0, v152, v10
	s_waitcnt lgkmcnt(1)
	v_lshlrev_b32_e32 v10, 16, v11
	v_fmac_f32_e32 v0, v151, v10
	s_waitcnt lgkmcnt(0)
	v_lshlrev_b32_e32 v10, 16, v12
	v_fmac_f32_e32 v0, v150, v10
	v_cvt_pk_bf16_f32 v10, v0, v1
	ds_write_b16 v146, v10 offset:29952
	ds_read_u16 v10, v61
	ds_write_b32 v145, v0 offset:17024
	ds_read_u16 v0, v62 offset:128
	ds_read_u16 v11, v62 offset:256
	ds_read_u16 v12, v62 offset:384
	s_waitcnt lgkmcnt(4)
	v_lshlrev_b32_e32 v10, 16, v10
	v_fma_f32 v10, v149, v10, v148
	s_waitcnt lgkmcnt(2)
	v_lshlrev_b32_e32 v0, 16, v0
	v_fmac_f32_e32 v10, v152, v0
	s_waitcnt lgkmcnt(1)
	v_lshlrev_b32_e32 v0, 16, v11
	v_fmac_f32_e32 v10, v151, v0
	s_waitcnt lgkmcnt(0)
	v_lshlrev_b32_e32 v0, 16, v12
	v_fmac_f32_e32 v10, v150, v0
	v_cvt_pk_bf16_f32 v0, v10, v1
	ds_write_b16 v146, v0 offset:31104
	ds_read_u16 v0, v63
	ds_write_b32 v145, v10 offset:19104
	ds_read_u16 v10, v64 offset:128
	ds_read_u16 v11, v64 offset:256
	ds_read_u16 v12, v64 offset:384
	s_waitcnt lgkmcnt(4)
	v_lshlrev_b32_e32 v0, 16, v0
	v_fma_f32 v0, v149, v0, v148
	s_waitcnt lgkmcnt(2)
	v_lshlrev_b32_e32 v10, 16, v10
	v_fmac_f32_e32 v0, v152, v10
	s_waitcnt lgkmcnt(1)
	v_lshlrev_b32_e32 v10, 16, v11
	v_fmac_f32_e32 v0, v151, v10
	s_waitcnt lgkmcnt(0)
	v_lshlrev_b32_e32 v10, 16, v12
	v_fmac_f32_e32 v0, v150, v10
	v_cvt_pk_bf16_f32 v10, v0, v1
	ds_write_b16 v146, v10 offset:32256
	ds_read_u16 v10, v65
	ds_write_b32 v145, v0 offset:21184
	ds_read_u16 v0, v66 offset:128
	ds_read_u16 v11, v66 offset:256
	ds_read_u16 v12, v66 offset:384
	s_waitcnt lgkmcnt(4)
	v_lshlrev_b32_e32 v10, 16, v10
	v_fma_f32 v10, v149, v10, v148
	s_waitcnt lgkmcnt(2)
	v_lshlrev_b32_e32 v0, 16, v0
	v_fmac_f32_e32 v10, v152, v0
	s_waitcnt lgkmcnt(1)
	v_lshlrev_b32_e32 v0, 16, v11
	v_fmac_f32_e32 v10, v151, v0
	s_waitcnt lgkmcnt(0)
	v_lshlrev_b32_e32 v0, 16, v12
	v_fmac_f32_e32 v10, v150, v0
	ds_write_b32 v145, v10 offset:23264
	v_cvt_pk_bf16_f32 v0, v10, v1
	ds_write_b16 v146, v0 offset:33408
	s_waitcnt lgkmcnt(0)
	s_barrier
; __device__ __forceinline__ float sigm(float x) { return __builtin_amdgcn_rcpf(1.0f + __expf(-x)); }
; template <int PASS>
; __device__ void lru_items(const Params& p, unsigned char* shm, int l) {
;     ...
;         { const int d = w >> 2, tt = w & 3;
;           const bf16x8 a0 = *(const bf16x8*)(xcb + (tt * 16 + fr) * 72 + fq * 8), a1 = *(const bf16x8*)(xcb + (tt * 16 + fr) * 72 + 32 + fq * 8);
; #pragma unroll
;           for (int jt = 0; jt < 4; ++jt) {
;               f32x4 accr = (f32x4){0.f, 0.f, 0.f, 0.f}, acci = (f32x4){0.f, 0.f, 0.f, 0.f};
;               const bf16_t* wr_ = wt + ((d * 2 + 0) * 64 + jt * 16 + fr) * 72 + fq * 8; const bf16_t* wi_ = wt + ((d * 2 + 1) * 64 + jt * 16 + fr) * 72 + fq * 8;
;               accr = __builtin_amdgcn_mfma_f32_16x16x32_bf16(a0, *(const bf16x8*)wr_, accr, 0, 0, 0);
;               accr = __builtin_amdgcn_mfma_f32_16x16x32_bf16(a1, *(const bf16x8*)(wr_ + 32), accr, 0, 0, 0);
;               acci = __builtin_amdgcn_mfma_f32_16x16x32_bf16(a0, *(const bf16x8*)wi_, acci, 0, 0, 0);
;               acci = __builtin_amdgcn_mfma_f32_16x16x32_bf16(a1, *(const bf16x8*)(wi_ + 32), acci, 0, 0, 0);
;               const int j = jt * 16 + fr;
; #pragma unroll
;               for (int i = 0; i < 4; ++i) { const int t = tt * 16 + fq * 4 + i;
;                   const float r = sigm(accr[i] + gba[jt]), ig = sigm(acci[i] + gbx[jt]), a = __expf(r * gsp[jt]);
;                   As[(d * 64 + t) * 64 + j] = a;
;                   Bs[(d * 64 + t) * 64 + j] = sqrtf(fmaxf(1.0f - a * a, 0.f)) * ig * xcf[t * 65 + j]; }
;           } }
	ds_read_b128 v[14:17], v44 offset:25344
	ds_read_b128 v[10:13], v44 offset:25408
	ds_read_b128 v[32:35], v67 offset:34560
	ds_read_b128 v[154:157], v67 offset:34624
	s_waitcnt lgkmcnt(1)
	v_mfma_f32_16x16x32_bf16 v[32:35], v[14:17], v[32:35], 0
	ds_read_b128 v[158:161], v68 offset:43840
	s_waitcnt lgkmcnt(1)
	v_mfma_f32_16x16x32_bf16 v[32:35], v[10:13], v[154:157], v[32:35]
	ds_read_b128 v[154:157], v68 offset:43776
	s_waitcnt lgkmcnt(0)
	v_mfma_f32_16x16x32_bf16 v[154:157], v[14:17], v[154:157], 0
	s_waitcnt vmcnt(7)
	s_nop 3
	v_add_f32_e32 v0, v22, v32
	v_mul_f32_e32 v0, 0xbfb8aa3b, v0
	v_exp_f32_e32 v0, v0
	v_mfma_f32_16x16x32_bf16 v[154:157], v[10:13], v[158:161], v[154:157]
	v_add_f32_e32 v33, v22, v33
	v_mul_f32_e32 v33, 0xbfb8aa3b, v33
	v_add_f32_e32 v0, 1.0, v0
	v_rcp_f32_e32 v0, v0
	v_exp_f32_e32 v33, v33
	s_waitcnt vmcnt(3)
	s_nop 1
	v_add_f32_e32 v32, v38, v154
	v_mul_f32_e32 v32, 0xbfb8aa3b, v32
	v_mul_f32_e32 v0, v19, v0
	v_mul_f32_e32 v0, 0x3fb8aa3b, v0
	v_exp_f32_e32 v0, v0
	v_exp_f32_e32 v32, v32
	v_add_f32_e32 v33, 1.0, v33
	v_rcp_f32_e32 v33, v33
	v_fma_f32 v37, -v0, v0, 1.0
	v_max_f32_e32 v37, 0, v37
	ds_write_b32 v69, v0
	v_add_f32_e32 v32, 1.0, v32
	v_sqrt_f32_e32 v41, v37
	v_rcp_f32_e32 v32, v32
	v_add_f32_e32 v34, v22, v34
	v_mul_f32_e32 v34, 0xbfb8aa3b, v34
	v_mov_b32_e32 v0, v41
	v_exp_f32_e32 v34, v34
	s_nop 1
	ds_read_b32 v41, v147 offset:8704
	s_nop 1
	v_mul_f32_e32 v0, v32, v0
	s_waitcnt lgkmcnt(0)
	v_mul_f32_e32 v0, v41, v0
	ds_write_b32 v70, v0
	v_mul_f32_e32 v0, v19, v33
	v_mul_f32_e32 v0, 0x3fb8aa3b, v0
	v_exp_f32_e32 v0, v0
	v_add_f32_e32 v32, v38, v155
	v_mul_f32_e32 v32, 0xbfb8aa3b, v32
	v_exp_f32_e32 v32, v32
	v_fma_f32 v33, -v0, v0, 1.0
	v_max_f32_e32 v33, 0, v33
	ds_write_b32 v71, v0
	v_add_f32_e32 v32, 1.0, v32
	v_sqrt_f32_e32 v37, v33
	v_rcp_f32_e32 v32, v32
	v_mov_b32_e32 v0, v37
	s_nop 0
	s_nop 1
	ds_read_b32 v37, v147 offset:8964
	s_nop 1
	v_add_f32_e32 v33, 1.0, v34
	v_rcp_f32_e32 v33, v33
	v_mul_f32_e32 v0, v32, v0
	s_waitcnt lgkmcnt(0)
	v_mul_f32_e32 v0, v37, v0
	ds_write_b32 v72, v0
	v_mul_f32_e32 v0, v19, v33
	v_mul_f32_e32 v0, 0x3fb8aa3b, v0
	v_exp_f32_e32 v0, v0
	v_add_f32_e32 v32, v38, v156
	v_mul_f32_e32 v32, 0xbfb8aa3b, v32
	v_exp_f32_e32 v32, v32
	v_fma_f32 v33, -v0, v0, 1.0
	v_max_f32_e32 v33, 0, v33
	ds_write_b32 v73, v0
	v_add_f32_e32 v32, 1.0, v32
	v_sqrt_f32_e32 v34, v33
	v_rcp_f32_e32 v32, v32
	v_mov_b32_e32 v0, v34
	s_nop 0
	s_nop 1
	v_add_f32_e32 v34, v22, v35
	v_mul_f32_e32 v34, 0xbfb8aa3b, v34
	v_exp_f32_e32 v34, v34
	ds_read_b32 v35, v147 offset:9224
	s_nop 1
	v_add_f32_e32 v33, 1.0, v34
	v_rcp_f32_e32 v33, v33
	v_mul_f32_e32 v0, v32, v0
	s_waitcnt lgkmcnt(0)
	v_mul_f32_e32 v0, v35, v0
	ds_write_b32 v74, v0
	v_mul_f32_e32 v0, v19, v33
	v_mul_f32_e32 v0, 0x3fb8aa3b, v0
	v_exp_f32_e32 v0, v0
	v_add_f32_e32 v32, v38, v157
	v_mul_f32_e32 v32, 0xbfb8aa3b, v32
	v_exp_f32_e32 v32, v32
	v_fma_f32 v33, -v0, v0, 1.0
	v_max_f32_e32 v33, 0, v33
	ds_write_b32 v75, v0
	v_add_f32_e32 v32, 1.0, v32
	v_sqrt_f32_e32 v34, v33
	v_rcp_f32_e32 v32, v32
	v_mov_b32_e32 v0, v34
	s_nop 0
	s_nop 1
	ds_read_b32 v35, v147 offset:9484
	s_nop 1
	v_mul_f32_e32 v0, v32, v0
	s_waitcnt lgkmcnt(0)
	v_mul_f32_e32 v0, v0, v35
	ds_write_b32 v76, v0
	ds_read_b128 v[32:35], v67 offset:36864
	ds_read_b128 v[154:157], v67 offset:36928
	s_waitcnt lgkmcnt(1)
	v_mfma_f32_16x16x32_bf16 v[32:35], v[14:17], v[32:35], 0
	ds_read_b128 v[158:161], v68 offset:46144
	s_waitcnt lgkmcnt(1)
	v_mfma_f32_16x16x32_bf16 v[32:35], v[10:13], v[154:157], v[32:35]
	ds_read_b128 v[154:157], v68 offset:46080
	s_waitcnt lgkmcnt(0)
	v_mfma_f32_16x16x32_bf16 v[154:157], v[14:17], v[154:157], 0
	s_nop 4
	v_add_f32_e32 v0, v23, v32
	v_mul_f32_e32 v0, 0xbfb8aa3b, v0
	v_exp_f32_e32 v0, v0
	v_mfma_f32_16x16x32_bf16 v[154:157], v[10:13], v[158:161], v[154:157]
	v_add_f32_e32 v33, v23, v33
	v_mul_f32_e32 v33, 0xbfb8aa3b, v33
	v_add_f32_e32 v0, 1.0, v0
	v_rcp_f32_e32 v0, v0
	v_exp_f32_e32 v33, v33
	s_waitcnt vmcnt(2)
	s_nop 1
	v_add_f32_e32 v32, v39, v154
	v_mul_f32_e32 v32, 0xbfb8aa3b, v32
	v_mul_f32_e32 v0, v18, v0
	v_mul_f32_e32 v0, 0x3fb8aa3b, v0
	v_exp_f32_e32 v0, v0
	v_exp_f32_e32 v32, v32
	v_add_f32_e32 v33, 1.0, v33
	v_rcp_f32_e32 v33, v33
	v_fma_f32 v37, -v0, v0, 1.0
	v_max_f32_e32 v37, 0, v37
	ds_write_b32 v77, v0
	v_add_f32_e32 v32, 1.0, v32
	v_sqrt_f32_e32 v41, v37
	v_rcp_f32_e32 v32, v32
	v_add_f32_e32 v34, v23, v34
	v_mul_f32_e32 v34, 0xbfb8aa3b, v34
	v_mov_b32_e32 v0, v41
	v_exp_f32_e32 v34, v34
	s_nop 1
	ds_read_b32 v41, v147 offset:8768
	s_nop 1
	v_mul_f32_e32 v0, v32, v0
	s_waitcnt lgkmcnt(0)
	v_mul_f32_e32 v0, v41, v0
	ds_write_b32 v78, v0
	v_mul_f32_e32 v0, v18, v33
	v_mul_f32_e32 v0, 0x3fb8aa3b, v0
	v_exp_f32_e32 v0, v0
	v_add_f32_e32 v32, v39, v155
	v_mul_f32_e32 v32, 0xbfb8aa3b, v32
	v_exp_f32_e32 v32, v32
	v_fma_f32 v33, -v0, v0, 1.0
	v_max_f32_e32 v33, 0, v33
	ds_write_b32 v79, v0
	v_add_f32_e32 v32, 1.0, v32
	v_sqrt_f32_e32 v37, v33
	v_rcp_f32_e32 v32, v32
	v_mov_b32_e32 v0, v37
	s_nop 0
	s_nop 1
	ds_read_b32 v37, v147 offset:9028
	s_nop 1
	v_add_f32_e32 v33, 1.0, v34
	v_rcp_f32_e32 v33, v33
	v_mul_f32_e32 v0, v32, v0
	s_waitcnt lgkmcnt(0)
	v_mul_f32_e32 v0, v37, v0
	ds_write_b32 v80, v0
	v_mul_f32_e32 v0, v18, v33
	v_mul_f32_e32 v0, 0x3fb8aa3b, v0
	v_exp_f32_e32 v0, v0
	v_add_f32_e32 v32, v39, v156
	v_mul_f32_e32 v32, 0xbfb8aa3b, v32
	v_exp_f32_e32 v32, v32
	v_fma_f32 v33, -v0, v0, 1.0
	v_max_f32_e32 v33, 0, v33
	ds_write_b32 v81, v0
	v_add_f32_e32 v32, 1.0, v32
	v_sqrt_f32_e32 v34, v33
	v_rcp_f32_e32 v32, v32
	v_mov_b32_e32 v0, v34
	s_nop 0
	s_nop 1
	v_add_f32_e32 v34, v23, v35
	v_mul_f32_e32 v34, 0xbfb8aa3b, v34
	v_exp_f32_e32 v34, v34
	ds_read_b32 v35, v147 offset:9288
	s_nop 1
	v_add_f32_e32 v33, 1.0, v34
	v_rcp_f32_e32 v33, v33
	v_mul_f32_e32 v0, v32, v0
	s_waitcnt lgkmcnt(0)
; __device__ __forceinline__ float sigm(float x) { return __builtin_amdgcn_rcpf(1.0f + __expf(-x)); }
; template <int PASS>
; __device__ void lru_items(const Params& p, unsigned char* shm, int l) {
;     ...
;           for (int jt = 0; jt < 4; ++jt) {
;               f32x4 accr = (f32x4){0.f, 0.f, 0.f, 0.f}, acci = (f32x4){0.f, 0.f, 0.f, 0.f};
;               const bf16_t* wr_ = wt + ((d * 2 + 0) * 64 + jt * 16 + fr) * 72 + fq * 8; const bf16_t* wi_ = wt + ((d * 2 + 1) * 64 + jt * 16 + fr) * 72 + fq * 8;
;               accr = __builtin_amdgcn_mfma_f32_16x16x32_bf16(a0, *(const bf16x8*)wr_, accr, 0, 0, 0);
;               accr = __builtin_amdgcn_mfma_f32_16x16x32_bf16(a1, *(const bf16x8*)(wr_ + 32), accr, 0, 0, 0);
;               acci = __builtin_amdgcn_mfma_f32_16x16x32_bf16(a0, *(const bf16x8*)wi_, acci, 0, 0, 0);
;               acci = __builtin_amdgcn_mfma_f32_16x16x32_bf16(a1, *(const bf16x8*)(wi_ + 32), acci, 0, 0, 0);
;               const int j = jt * 16 + fr;
; #pragma unroll
;               for (int i = 0; i < 4; ++i) { const int t = tt * 16 + fq * 4 + i;
;                   const float r = sigm(accr[i] + gba[jt]), ig = sigm(acci[i] + gbx[jt]), a = __expf(r * gsp[jt]);
;                   As[(d * 64 + t) * 64 + j] = a;
;                   Bs[(d * 64 + t) * 64 + j] = sqrtf(fmaxf(1.0f - a * a, 0.f)) * ig * xcf[t * 65 + j]; }
;           } }
	v_mul_f32_e32 v0, v35, v0
	ds_write_b32 v82, v0
	v_mul_f32_e32 v0, v18, v33
	v_mul_f32_e32 v0, 0x3fb8aa3b, v0
	v_exp_f32_e32 v0, v0
	v_add_f32_e32 v32, v39, v157
	v_mul_f32_e32 v32, 0xbfb8aa3b, v32
	v_exp_f32_e32 v32, v32
	v_fma_f32 v33, -v0, v0, 1.0
	v_max_f32_e32 v33, 0, v33
	ds_write_b32 v83, v0
	v_add_f32_e32 v32, 1.0, v32
	v_sqrt_f32_e32 v34, v33
	v_rcp_f32_e32 v32, v32
	v_mov_b32_e32 v0, v34
	s_nop 0
	s_nop 1
	ds_read_b32 v35, v147 offset:9548
	s_nop 1
	v_mul_f32_e32 v0, v32, v0
	s_waitcnt lgkmcnt(0)
	v_mul_f32_e32 v0, v0, v35
	ds_write_b32 v84, v0
	ds_read_b128 v[32:35], v67 offset:39168
	ds_read_b128 v[154:157], v67 offset:39232
	s_waitcnt lgkmcnt(1)
	v_mfma_f32_16x16x32_bf16 v[32:35], v[14:17], v[32:35], 0
	ds_read_b128 v[158:161], v68 offset:48448
	s_waitcnt lgkmcnt(1)
	v_mfma_f32_16x16x32_bf16 v[32:35], v[10:13], v[154:157], v[32:35]
	ds_read_b128 v[154:157], v68 offset:48384
	s_waitcnt lgkmcnt(0)
	v_mfma_f32_16x16x32_bf16 v[154:157], v[14:17], v[154:157], 0
	s_nop 4
	v_add_f32_e32 v0, v24, v32
	v_mul_f32_e32 v0, 0xbfb8aa3b, v0
	v_exp_f32_e32 v0, v0
	v_mfma_f32_16x16x32_bf16 v[154:157], v[10:13], v[158:161], v[154:157]
	v_add_f32_e32 v33, v24, v33
	v_mul_f32_e32 v33, 0xbfb8aa3b, v33
	v_add_f32_e32 v0, 1.0, v0
	v_rcp_f32_e32 v0, v0
	v_exp_f32_e32 v33, v33
	s_waitcnt vmcnt(1)
	s_nop 1
	v_add_f32_e32 v32, v40, v154
	v_mul_f32_e32 v32, 0xbfb8aa3b, v32
	v_mul_f32_e32 v0, v21, v0
	v_mul_f32_e32 v0, 0x3fb8aa3b, v0
	v_exp_f32_e32 v0, v0
	v_exp_f32_e32 v32, v32
	v_add_f32_e32 v33, 1.0, v33
	v_rcp_f32_e32 v33, v33
	v_fma_f32 v37, -v0, v0, 1.0
	v_max_f32_e32 v37, 0, v37
	ds_write_b32 v85, v0
	v_add_f32_e32 v32, 1.0, v32
	v_sqrt_f32_e32 v41, v37
	v_rcp_f32_e32 v32, v32
	v_add_f32_e32 v34, v24, v34
	v_mul_f32_e32 v34, 0xbfb8aa3b, v34
	v_mov_b32_e32 v0, v41
	v_exp_f32_e32 v34, v34
	s_nop 1
	ds_read_b32 v41, v147 offset:8832
	s_nop 1
	v_mul_f32_e32 v0, v32, v0
	s_waitcnt lgkmcnt(0)
	v_mul_f32_e32 v0, v41, v0
	ds_write_b32 v86, v0
	v_mul_f32_e32 v0, v21, v33
	v_mul_f32_e32 v0, 0x3fb8aa3b, v0
	v_exp_f32_e32 v0, v0
	v_add_f32_e32 v32, v40, v155
	v_mul_f32_e32 v32, 0xbfb8aa3b, v32
	v_exp_f32_e32 v32, v32
	v_fma_f32 v33, -v0, v0, 1.0
	v_max_f32_e32 v33, 0, v33
	ds_write_b32 v87, v0
	v_add_f32_e32 v32, 1.0, v32
	v_sqrt_f32_e32 v37, v33
	v_rcp_f32_e32 v32, v32
	v_mov_b32_e32 v0, v37
	s_nop 0
	s_nop 1
	ds_read_b32 v37, v147 offset:9092
	s_nop 1
	v_add_f32_e32 v33, 1.0, v34
	v_rcp_f32_e32 v33, v33
	v_mul_f32_e32 v0, v32, v0
	s_waitcnt lgkmcnt(0)
	v_mul_f32_e32 v0, v37, v0
	ds_write_b32 v88, v0
	v_mul_f32_e32 v0, v21, v33
	v_mul_f32_e32 v0, 0x3fb8aa3b, v0
	v_exp_f32_e32 v0, v0
	v_add_f32_e32 v32, v40, v156
	v_mul_f32_e32 v32, 0xbfb8aa3b, v32
	v_exp_f32_e32 v32, v32
	v_fma_f32 v33, -v0, v0, 1.0
	v_max_f32_e32 v33, 0, v33
	ds_write_b32 v89, v0
	v_add_f32_e32 v32, 1.0, v32
	v_sqrt_f32_e32 v34, v33
	v_rcp_f32_e32 v32, v32
	v_mov_b32_e32 v0, v34
	s_nop 0
	s_nop 1
	v_add_f32_e32 v34, v24, v35
	v_mul_f32_e32 v34, 0xbfb8aa3b, v34
	v_exp_f32_e32 v34, v34
	ds_read_b32 v35, v147 offset:9352
	s_nop 1
	v_add_f32_e32 v33, 1.0, v34
	v_rcp_f32_e32 v33, v33
	v_mul_f32_e32 v0, v32, v0
	s_waitcnt lgkmcnt(0)
	v_mul_f32_e32 v0, v35, v0
	ds_write_b32 v90, v0
	v_mul_f32_e32 v0, v21, v33
	v_mul_f32_e32 v0, 0x3fb8aa3b, v0
	v_exp_f32_e32 v0, v0
	v_add_f32_e32 v32, v40, v157
	v_mul_f32_e32 v32, 0xbfb8aa3b, v32
	v_exp_f32_e32 v32, v32
	v_fma_f32 v33, -v0, v0, 1.0
	v_max_f32_e32 v33, 0, v33
	ds_write_b32 v91, v0
	v_add_f32_e32 v32, 1.0, v32
	v_sqrt_f32_e32 v34, v33
	v_rcp_f32_e32 v32, v32
	v_mov_b32_e32 v0, v34
	s_nop 0
	s_nop 1
	ds_read_b32 v35, v147 offset:9612
	s_nop 1
	v_mul_f32_e32 v0, v32, v0
	s_waitcnt lgkmcnt(0)
	v_mul_f32_e32 v0, v0, v35
	ds_write_b32 v92, v0
	ds_read_b128 v[32:35], v67 offset:41472
	ds_read_b128 v[154:157], v67 offset:41536
	s_waitcnt lgkmcnt(1)
	v_mfma_f32_16x16x32_bf16 v[32:35], v[14:17], v[32:35], 0
	ds_read_b128 v[158:161], v68 offset:50752
	s_waitcnt lgkmcnt(1)
	v_mfma_f32_16x16x32_bf16 v[32:35], v[10:13], v[154:157], v[32:35]
	ds_read_b128 v[154:157], v68 offset:50688
	s_waitcnt lgkmcnt(0)
	v_mfma_f32_16x16x32_bf16 v[14:17], v[14:17], v[154:157], 0
	s_nop 4
	v_add_f32_e32 v0, v25, v32
	v_mul_f32_e32 v0, 0xbfb8aa3b, v0
	v_exp_f32_e32 v0, v0
	v_mfma_f32_16x16x32_bf16 v[10:13], v[10:13], v[158:161], v[14:17]
	v_add_f32_e32 v0, 1.0, v0
	v_rcp_f32_e32 v0, v0
	s_nop 0
	v_mul_f32_e32 v0, v20, v0
	v_mul_f32_e32 v0, 0x3fb8aa3b, v0
	v_exp_f32_e32 v0, v0
	s_waitcnt vmcnt(0)
	s_nop 0
	v_add_f32_e32 v10, v36, v10
	v_mul_f32_e32 v10, 0xbfb8aa3b, v10
	v_exp_f32_e32 v10, v10
	v_fma_f32 v14, -v0, v0, 1.0
	v_max_f32_e32 v14, 0, v14
	ds_write_b32 v93, v0
	v_add_f32_e32 v10, 1.0, v10
	v_sqrt_f32_e32 v15, v14
	v_rcp_f32_e32 v10, v10
	v_mov_b32_e32 v0, v15
	s_nop 0
	s_nop 1
	v_add_f32_e32 v15, v25, v33
	v_mul_f32_e32 v15, 0xbfb8aa3b, v15
	v_exp_f32_e32 v15, v15
	ds_read_b32 v16, v147 offset:8896
	s_nop 1
	v_add_f32_e32 v14, 1.0, v15
	v_rcp_f32_e32 v14, v14
	v_mul_f32_e32 v0, v10, v0
	s_waitcnt lgkmcnt(0)
	v_mul_f32_e32 v0, v16, v0
	ds_write_b32 v94, v0
	v_mul_f32_e32 v0, v20, v14
	v_mul_f32_e32 v0, 0x3fb8aa3b, v0
	v_exp_f32_e32 v0, v0
	v_add_f32_e32 v10, v36, v11
	v_mul_f32_e32 v10, 0xbfb8aa3b, v10
	v_exp_f32_e32 v10, v10
	v_fma_f32 v11, -v0, v0, 1.0
	v_max_f32_e32 v11, 0, v11
	ds_write_b32 v95, v0
	v_add_f32_e32 v10, 1.0, v10
	v_sqrt_f32_e32 v14, v11
	v_rcp_f32_e32 v10, v10
	v_mov_b32_e32 v0, v14
	s_nop 0
	s_nop 1
	v_add_f32_e32 v14, v25, v34
	v_mul_f32_e32 v14, 0xbfb8aa3b, v14
	v_exp_f32_e32 v14, v14
	ds_read_b32 v15, v147 offset:9156
	s_nop 1
	v_add_f32_e32 v11, 1.0, v14
	v_rcp_f32_e32 v11, v11
	v_mul_f32_e32 v0, v10, v0
	s_waitcnt lgkmcnt(0)
	v_mul_f32_e32 v0, v15, v0
	ds_write_b32 v96, v0
	v_mul_f32_e32 v0, v20, v11
	v_mul_f32_e32 v0, 0x3fb8aa3b, v0
	v_exp_f32_e32 v0, v0
	v_add_f32_e32 v10, v36, v12
	v_mul_f32_e32 v10, 0xbfb8aa3b, v10
	v_exp_f32_e32 v10, v10
	v_fma_f32 v11, -v0, v0, 1.0
	v_max_f32_e32 v11, 0, v11
	ds_write_b32 v97, v0
	v_add_f32_e32 v10, 1.0, v10
	v_sqrt_f32_e32 v12, v11
	v_rcp_f32_e32 v10, v10
	v_mov_b32_e32 v0, v12
	s_nop 0
	s_nop 1
	v_add_f32_e32 v12, v25, v35
	v_mul_f32_e32 v12, 0xbfb8aa3b, v12
	v_exp_f32_e32 v12, v12
	ds_read_b32 v14, v147 offset:9416
	s_nop 1
	v_add_f32_e32 v11, 1.0, v12
	v_rcp_f32_e32 v11, v11
	v_mul_f32_e32 v0, v10, v0
	s_waitcnt lgkmcnt(0)
	v_mul_f32_e32 v0, v14, v0
	ds_write_b32 v98, v0
	v_mul_f32_e32 v0, v20, v11
	v_mul_f32_e32 v0, 0x3fb8aa3b, v0
	v_exp_f32_e32 v0, v0
	v_add_f32_e32 v10, v36, v13
	v_mul_f32_e32 v10, 0xbfb8aa3b, v10
	v_exp_f32_e32 v10, v10
	v_fma_f32 v11, -v0, v0, 1.0
	v_max_f32_e32 v11, 0, v11
	ds_write_b32 v99, v0
	v_add_f32_e32 v10, 1.0, v10
	v_sqrt_f32_e32 v12, v11
	v_rcp_f32_e32 v10, v10
	v_mov_b32_e32 v0, v12
	s_nop 0
	s_nop 1
	ds_read_b32 v13, v147 offset:9676
	s_nop 1
	v_mul_f32_e32 v0, v10, v0
	s_waitcnt lgkmcnt(0)
	v_mul_f32_e32 v0, v0, v13
	ds_write_b32 v100, v0
	s_waitcnt lgkmcnt(0)
	s_barrier
; template <int PASS>
; __device__ void lru_items(const Params& p, unsigned char* shm, int l) {
;     ...
;         {
;             const int seg = tid >> 7, d = (tid >> 6) & 1, j = tid & 63;
;             float h = 0.f, P = 1.f;
; #pragma unroll
;             for (int s = 0; s < 16; ++s) { const int st = seg * 16 + s, t = d ? 63 - st : st; const float a = As[(d * 64 + t) * 64 + j]; h = a * h + Bs[(d * 64 + t) * 64 + j]; P *= a; }
;             Pq[seg * 128 + (tid & 127)] = P; Hq[seg * 128 + (tid & 127)] = h;
;             __syncthreads();
;             if (PASS == 0) {
;                 if (tid < 128) { float hh = Hq[tid], PP = Pq[tid];
; #pragma unroll
;                     for (int q = 1; q < 4; ++q) { const float pq = Pq[q * 128 + tid]; hh = pq * hh + Hq[q * 128 + tid]; PP *= pq; }
;                     SA[so] = PP; SH[so] = hh; }
	ds_read_b32 v0, v101
	ds_read_b32 v10, v102
	ds_read_b32 v11, v103
	ds_read_b32 v12, v104
	ds_read_b32 v13, v105
	ds_read_b32 v14, v106
	ds_read_b32 v15, v107
	ds_read_b32 v16, v108
	s_waitcnt lgkmcnt(6)
	v_fmac_f32_e32 v10, 0, v0
	s_waitcnt lgkmcnt(4)
	v_fmac_f32_e32 v12, v10, v11
	v_mul_f32_e32 v0, v0, v11
	s_waitcnt lgkmcnt(2)
	v_fmac_f32_e32 v14, v12, v13
	v_mul_f32_e32 v0, v0, v13
	s_waitcnt lgkmcnt(0)
	v_fmac_f32_e32 v16, v14, v15
	v_mul_f32_e32 v0, v0, v15
	ds_read_b32 v10, v109
	ds_read_b32 v11, v110
	ds_read_b32 v12, v111
	ds_read_b32 v13, v112
	ds_read_b32 v14, v113
	ds_read_b32 v15, v114
	ds_read_b32 v17, v115
	ds_read_b32 v32, v116
	s_waitcnt lgkmcnt(6)
	v_fmac_f32_e32 v11, v16, v10
	v_mul_f32_e32 v0, v0, v10
	s_waitcnt lgkmcnt(4)
	v_fmac_f32_e32 v13, v11, v12
	v_mul_f32_e32 v0, v0, v12
	s_waitcnt lgkmcnt(2)
	v_fmac_f32_e32 v15, v13, v14
	v_mul_f32_e32 v0, v0, v14
	s_waitcnt lgkmcnt(0)
	v_fmac_f32_e32 v32, v15, v17
	v_mul_f32_e32 v0, v0, v17
	ds_read_b32 v10, v117
	ds_read_b32 v11, v118
	ds_read_b32 v12, v119
	ds_read_b32 v13, v120
	ds_read_b32 v14, v121
	ds_read_b32 v15, v122
	ds_read_b32 v16, v123
	ds_read_b32 v17, v124
	s_waitcnt lgkmcnt(6)
	v_fmac_f32_e32 v11, v32, v10
	v_mul_f32_e32 v0, v0, v10
	s_waitcnt lgkmcnt(4)
	v_fmac_f32_e32 v13, v11, v12
	v_mul_f32_e32 v0, v0, v12
	s_waitcnt lgkmcnt(2)
	v_fmac_f32_e32 v15, v13, v14
	v_mul_f32_e32 v0, v0, v14
	s_waitcnt lgkmcnt(0)
	v_fmac_f32_e32 v17, v15, v16
	v_mul_f32_e32 v0, v0, v16
	ds_read_b32 v10, v125
	ds_read_b32 v11, v126
	ds_read_b32 v12, v127
	ds_read_b32 v13, v128
	ds_read_b32 v14, v129
	ds_read_b32 v15, v131
	ds_read_b32 v16, v132
	ds_read_b32 v32, v133
	s_waitcnt lgkmcnt(7)
	v_mul_f32_e32 v0, v0, v10
	s_waitcnt lgkmcnt(6)
	v_fmac_f32_e32 v11, v17, v10
	s_waitcnt lgkmcnt(5)
	v_mul_f32_e32 v0, v0, v12
	s_waitcnt lgkmcnt(4)
	v_fmac_f32_e32 v13, v11, v12
	s_waitcnt lgkmcnt(3)
	v_mul_f32_e32 v0, v0, v14
	s_waitcnt lgkmcnt(2)
	v_fmac_f32_e32 v15, v13, v14
	s_waitcnt lgkmcnt(1)
	v_mul_f32_e32 v0, v0, v16
	s_waitcnt lgkmcnt(0)
	v_fmac_f32_e32 v32, v15, v16
	ds_write_b32 v45, v0
	ds_write_b32 v46, v32
	s_waitcnt lgkmcnt(0)
	s_barrier
	s_and_saveexec_b64 s[40:41], s[38:39]
	s_cbranch_execz .LBB0_295
	ds_read_b32 v0, v46
	ds_read_b32 v12, v45
	ds_read_b32 v13, v134
	ds_read_b32 v14, v135
	s_ashr_i32 s0, s2, 3
	v_and_or_b32 v10, s0, -2, v43
	v_ashrrev_i32_e32 v11, 31, v10
	s_mov_b32 s51, s49
	s_waitcnt lgkmcnt(0)
	v_fmac_f32_e32 v14, v0, v13
	v_mul_f32_e32 v0, v12, v13
	ds_read_b32 v12, v136
	ds_read_b32 v13, v137
	v_lshlrev_b64 v[10:11], 10, v[10:11]
	v_lshl_add_u64 v[10:11], v[10:11], 0, s[50:51]
	v_or_b32_e32 v10, v10, v26
	s_waitcnt lgkmcnt(1)
	v_mul_f32_e32 v0, v0, v12
	s_waitcnt lgkmcnt(0)
	v_fmac_f32_e32 v13, v14, v12
	ds_read_b32 v12, v138
	ds_read_b32 v14, v139
	v_lshlrev_b64 v[10:11], 2, v[10:11]
	s_movk_i32 s23, 0xff7f
	v_readlane_b32 s22, v254, 8
	s_movk_i32 s17, 0x84
	s_mov_b32 s15, 0xfe03f81
	s_movk_i32 s10, 0xc00
	s_waitcnt lgkmcnt(0)
	v_fmac_f32_e32 v14, v13, v12
	v_mul_f32_e32 v0, v0, v12
	v_lshl_add_u64 v[12:13], s[34:35], 0, v[10:11]
	v_lshl_add_u64 v[10:11], s[96:97], 0, v[10:11]
	global_store_dword v[12:13], v0, off
	global_store_dword v[10:11], v14, off
	s_branch .LBB0_295
